# modnorm items: rows 2-4 of an item requested together with its first loads (three more rows in flight per wave), counted waits at first use
# baseline (speedup 1.0000x reference)
.LBB0_134:
	v_add_u32_e32 v22, v56, v63
	v_lshrrev_b32_e32 v15, 12, v63
	v_add_u32_e32 v14, 0x2000, v22
	v_add_u32_e32 v15, 1, v15
	v_cmp_gt_i32_e32 vcc, s17, v14
	v_add_u32_e32 v16, 0x2001, v22
	v_add_u32_e32 v18, 0x2002, v22
	v_add_u32_e32 v48, 0x2003, v22
	v_cndmask_b32_e64 v20, v15, 0, vcc
	v_ashrrev_i32_e32 v15, 31, v14
	v_add_u32_e32 v24, 1, v22
	v_add_u32_e32 v26, 2, v22
	v_add_u32_e32 v28, 3, v22
	v_ashrrev_i32_e32 v17, 31, v16
	v_cmp_gt_i32_e64 s[0:1], s17, v16
	v_ashrrev_i32_e32 v19, 31, v18
	v_cmp_gt_i32_e64 s[4:5], s17, v18
	v_ashrrev_i32_e32 v49, 31, v48
	v_cmp_gt_i32_e64 s[6:7], s17, v48
	v_mad_u64_u32 v[20:21], s[22:23], v20, s18, v[40:41]
	v_cndmask_b32_e32 v23, 0, v15, vcc
	v_cndmask_b32_e32 v22, v22, v14, vcc
	v_cndmask_b32_e32 v51, v64, v65, vcc
	v_cndmask_b32_e32 v50, v67, v68, vcc
	v_cndmask_b32_e64 v25, 0, v17, s[0:1]
	v_cndmask_b32_e64 v24, v24, v16, s[0:1]
	v_cndmask_b32_e64 v27, 0, v19, s[4:5]
	v_cndmask_b32_e64 v26, v26, v18, s[4:5]
	v_cndmask_b32_e64 v29, 0, v49, s[6:7]
	v_cndmask_b32_e64 v28, v28, v48, s[6:7]
	v_lshl_add_u64 v[74:75], v[20:21], 0, s[14:15]
	v_lshlrev_b64 v[76:77], 12, v[22:23]
	v_lshlrev_b64 v[14:15], 11, v[14:15]
	v_cndmask_b32_e64 v53, v64, v65, s[0:1]
	v_cndmask_b32_e64 v52, v67, v68, s[0:1]
	v_lshlrev_b64 v[16:17], 11, v[16:17]
	v_cndmask_b32_e64 v71, v64, v65, s[4:5]
	v_cndmask_b32_e64 v70, v67, v68, s[4:5]
	v_lshlrev_b64 v[18:19], 11, v[18:19]
	v_cndmask_b32_e64 v73, v64, v65, s[6:7]
	v_cndmask_b32_e64 v72, v67, v68, s[6:7]
	v_lshl_add_u64 v[20:21], v[20:21], 0, v[34:35]
	v_lshlrev_b64 v[78:79], 12, v[24:25]
	v_lshlrev_b64 v[80:81], 12, v[26:27]
	v_lshlrev_b64 v[82:83], 12, v[28:29]
	v_lshl_add_u64 v[84:85], v[74:75], 0, v[34:35]
	v_lshl_add_u64 v[50:51], v[50:51], 0, v[76:77]
	s_barrier
	global_load_dwordx4 v[2:5], v[36:37], off
	global_load_dwordx4 v[6:9], v[36:37], off offset:1024
	global_load_dwordx4 v[10:13], v[36:37], off offset:2048
	global_load_dwordx4 v[30:33], v[36:37], off offset:3072
	v_lshl_add_u64 v[102:103], v[38:39], 0, v[14:15]
	v_lshl_add_u64 v[104:105], v[38:39], 0, v[16:17]
	v_lshl_add_u64 v[54:55], v[38:39], 0, v[18:19]
	global_load_dwordx4 v[22:25], v[20:21], off
	global_load_dwordx4 v[14:17], v[20:21], off offset:1024
	v_lshl_add_u64 v[86:87], v[74:75], 0, v[42:43]
	v_lshl_add_u64 v[88:89], v[74:75], 0, v[44:45]
	global_load_dwordx4 v[26:29], v[20:21], off offset:2048
	s_nop 0
	global_load_dwordx4 v[18:21], v[20:21], off offset:3072
	v_lshl_add_u64 v[90:91], v[74:75], 0, v[46:47]
	v_lshl_add_u64 v[52:53], v[52:53], 0, v[78:79]
	v_lshl_add_u64 v[92:93], v[70:71], 0, v[80:81]
	v_lshl_add_u64 v[94:95], v[72:73], 0, v[82:83]
	global_load_dwordx4 v[70:73], v[84:85], off
	global_load_dwordx4 v[74:77], v[86:87], off
	global_load_dwordx4 v[78:81], v[88:89], off
	s_nop 0
	global_load_dwordx4 v[82:85], v[90:91], off
	v_lshl_add_u64 v[50:51], v[50:51], 0, v[34:35]
	v_lshl_add_u64 v[106:107], v[52:53], 0, v[34:35]
	v_lshl_add_u64 v[108:109], v[92:93], 0, v[34:35]
	v_lshl_add_u64 v[52:53], v[94:95], 0, v[34:35]
	global_load_dwordx4 v[86:89], v[50:51], off
	global_load_dwordx4 v[90:93], v[50:51], off offset:1024
	global_load_dwordx4 v[94:97], v[50:51], off offset:2048
	global_load_dwordx4 v[98:101], v[50:51], off offset:3072
	global_load_dwordx4 v[214:217], v[106:107], off
	global_load_dwordx4 v[218:221], v[106:107], off offset:1024
	global_load_dwordx4 v[222:225], v[106:107], off offset:2048
	global_load_dwordx4 v[226:229], v[106:107], off offset:3072
	global_load_dwordx4 v[230:233], v[108:109], off
	global_load_dwordx4 v[234:237], v[108:109], off offset:1024
	global_load_dwordx4 v[238:241], v[108:109], off offset:2048
	global_load_dwordx4 v[200:203], v[108:109], off offset:3072
	global_load_dwordx4 v[204:207], v[52:53], off
	global_load_dwordx4 v[208:211], v[52:53], off offset:1024
	global_load_dwordx4 v[246:249], v[52:53], off offset:2048
	global_load_dwordx4 v[250:253], v[52:53], off offset:3072
	v_add_u32_e32 v66, s3, v66
	v_add_u32_e32 v63, s16, v63
	s_waitcnt vmcnt(19)
	v_pk_add_f32 v[50:51], v[72:73], 1.0 op_sel_hi:[1,0]
	v_pk_add_f32 v[70:71], v[70:71], 1.0 op_sel_hi:[1,0]
	s_waitcnt vmcnt(18)
	v_pk_add_f32 v[72:73], v[76:77], 1.0 op_sel_hi:[1,0]
	v_pk_add_f32 v[74:75], v[74:75], 1.0 op_sel_hi:[1,0]
	s_waitcnt vmcnt(17)
	v_pk_add_f32 v[76:77], v[80:81], 1.0 op_sel_hi:[1,0]
	v_pk_add_f32 v[78:79], v[78:79], 1.0 op_sel_hi:[1,0]
	s_waitcnt vmcnt(16)
	v_pk_add_f32 v[80:81], v[84:85], 1.0 op_sel_hi:[1,0]
	v_pk_add_f32 v[82:83], v[82:83], 1.0 op_sel_hi:[1,0]
	s_waitcnt vmcnt(15)
	v_mov_b32_e32 v84, v87
	s_waitcnt vmcnt(14)
	v_mov_b32_e32 v85, v91
	v_pk_mul_f32 v[4:5], v[4:5], v[50:51]
	v_pk_mul_f32 v[50:51], v[2:3], v[70:71]
	v_pk_mul_f32 v[2:3], v[8:9], v[72:73]
	v_pk_mul_f32 v[6:7], v[6:7], v[74:75]
	v_mov_b32_e32 v74, v86
	v_mov_b32_e32 v75, v90
	v_pk_mul_f32 v[8:9], v[12:13], v[76:77]
	v_pk_mul_f32 v[12:13], v[10:11], v[78:79]
	v_pk_mul_f32 v[10:11], v[32:33], v[80:81]
	v_pk_mul_f32 v[30:31], v[30:31], v[82:83]
	s_waitcnt vmcnt(13)
	v_mov_b32_e32 v80, v95
	s_waitcnt vmcnt(12)
	v_mov_b32_e32 v81, v99
	v_pk_mul_f32 v[82:83], v[84:85], v[84:85]
	v_mov_b32_e32 v70, v88
	v_mov_b32_e32 v71, v92
	v_mov_b32_e32 v78, v94
	v_mov_b32_e32 v79, v98
	v_pk_mul_f32 v[80:81], v[80:81], v[80:81]
	v_pk_fma_f32 v[74:75], v[74:75], v[74:75], v[82:83]
	v_mov_b32_e32 v72, v89
	v_mov_b32_e32 v73, v93
	v_mov_b32_e32 v32, v96
	v_mov_b32_e32 v33, v100
	v_pk_fma_f32 v[78:79], v[78:79], v[78:79], v[80:81]
	v_pk_fma_f32 v[70:71], v[70:71], v[70:71], v[74:75]
	v_mov_b32_e32 v76, v97
	v_mov_b32_e32 v77, v101
	v_pk_fma_f32 v[32:33], v[32:33], v[32:33], v[78:79]
	v_pk_fma_f32 v[70:71], v[72:73], v[72:73], v[70:71]
	v_pk_fma_f32 v[32:33], v[76:77], v[76:77], v[32:33]
	v_add_f32_e32 v70, v70, v71
	v_add_f32_e32 v32, v70, v32
	v_add_f32_e32 v32, v32, v33
	ds_bpermute_b32 v33, v57, v32
	s_waitcnt lgkmcnt(0)
	v_add_f32_e32 v32, v32, v33
	ds_bpermute_b32 v33, v58, v32
	s_waitcnt lgkmcnt(0)
	v_add_f32_e32 v32, v32, v33
	ds_bpermute_b32 v33, v59, v32
	s_waitcnt lgkmcnt(0)
	v_add_f32_e32 v32, v32, v33
	ds_bpermute_b32 v33, v60, v32
	s_waitcnt lgkmcnt(0)
	v_add_f32_e32 v32, v32, v33
	ds_bpermute_b32 v33, v61, v32
	s_waitcnt lgkmcnt(0)
	v_add_f32_e32 v32, v32, v33
	ds_bpermute_b32 v33, v62, v32
	s_waitcnt lgkmcnt(0)
	v_add_f32_e32 v32, v32, v33
	v_fmamk_f32 v32, v32, 0x3a800000, v69
	v_mul_f32_e32 v33, 0x4b800000, v32
	v_cmp_gt_f32_e32 vcc, s19, v32
	s_nop 1
	v_cndmask_b32_e32 v32, v32, v33, vcc
	v_rsq_f32_e32 v32, v32
	s_nop 0
	v_mul_f32_e32 v33, 0x45800000, v32
	v_cndmask_b32_e32 v32, v32, v33, vcc
	v_pk_mul_f32 v[70:71], v[86:87], v[32:33] op_sel_hi:[1,0]
	v_pk_mul_f32 v[72:73], v[88:89], v[32:33] op_sel_hi:[1,0]
	v_pk_mul_f32 v[74:75], v[90:91], v[32:33] op_sel_hi:[1,0]
	v_pk_mul_f32 v[76:77], v[92:93], v[32:33] op_sel_hi:[1,0]
	v_pk_mul_f32 v[78:79], v[94:95], v[32:33] op_sel_hi:[1,0]
	v_pk_mul_f32 v[80:81], v[96:97], v[32:33] op_sel_hi:[1,0]
	v_pk_mul_f32 v[82:83], v[98:99], v[32:33] op_sel_hi:[1,0]
	v_pk_mul_f32 v[32:33], v[100:101], v[32:33] op_sel_hi:[1,0]
	v_pk_fma_f32 v[70:71], v[50:51], v[70:71], v[22:23]
	v_pk_fma_f32 v[72:73], v[4:5], v[72:73], v[24:25]
	v_pk_fma_f32 v[74:75], v[6:7], v[74:75], v[14:15]
	v_pk_fma_f32 v[76:77], v[2:3], v[76:77], v[16:17]
	v_pk_fma_f32 v[78:79], v[12:13], v[78:79], v[26:27]
	v_pk_fma_f32 v[80:81], v[8:9], v[80:81], v[28:29]
	v_pk_fma_f32 v[82:83], v[30:31], v[82:83], v[18:19]
	v_pk_fma_f32 v[32:33], v[10:11], v[32:33], v[20:21]
	v_cvt_pk_bf16_f32 v70, v70, v71
	v_cvt_pk_bf16_f32 v71, v72, v73
	v_cvt_pk_bf16_f32 v72, v74, v75
	v_cvt_pk_bf16_f32 v73, v76, v77
	v_cvt_pk_bf16_f32 v74, v78, v79
	v_cvt_pk_bf16_f32 v75, v80, v81
	v_cvt_pk_bf16_f32 v76, v82, v83
	v_cvt_pk_bf16_f32 v77, v32, v33
	global_store_dwordx2 v[102:103], v[70:71], off
	global_store_dwordx2 v[102:103], v[72:73], off offset:512
	global_store_dwordx2 v[102:103], v[74:75], off offset:1024
	global_store_dwordx2 v[102:103], v[76:77], off offset:1536
	s_waitcnt vmcnt(15)
	v_mov_b32_e32 v90, v215
	s_waitcnt vmcnt(14)
	v_mov_b32_e32 v91, v219
	v_mov_b32_e32 v88, v214
	v_mov_b32_e32 v89, v218
	s_waitcnt vmcnt(13)
	v_mov_b32_e32 v98, v223
	s_waitcnt vmcnt(12)
	v_mov_b32_e32 v99, v227
	v_pk_mul_f32 v[90:91], v[90:91], v[90:91]
	v_mov_b32_e32 v32, v216
	v_mov_b32_e32 v33, v220
	v_mov_b32_e32 v96, v222
	v_mov_b32_e32 v97, v226
	v_pk_mul_f32 v[98:99], v[98:99], v[98:99]
	v_pk_fma_f32 v[88:89], v[88:89], v[88:89], v[90:91]
	v_mov_b32_e32 v86, v217
	v_mov_b32_e32 v87, v221
	v_mov_b32_e32 v92, v224
	v_mov_b32_e32 v93, v228
	v_pk_fma_f32 v[90:91], v[96:97], v[96:97], v[98:99]
	v_pk_fma_f32 v[32:33], v[32:33], v[32:33], v[88:89]
	v_mov_b32_e32 v94, v225
	v_mov_b32_e32 v95, v229
	v_pk_fma_f32 v[88:89], v[92:93], v[92:93], v[90:91]
	v_pk_fma_f32 v[32:33], v[86:87], v[86:87], v[32:33]
	v_pk_fma_f32 v[86:87], v[94:95], v[94:95], v[88:89]
	v_add_f32_e32 v32, v32, v33
	v_add_f32_e32 v32, v32, v86
	v_add_f32_e32 v32, v32, v87
	ds_bpermute_b32 v33, v57, v32
	s_waitcnt lgkmcnt(0)
	v_add_f32_e32 v32, v32, v33
	ds_bpermute_b32 v33, v58, v32
	s_waitcnt lgkmcnt(0)
	v_add_f32_e32 v32, v32, v33
	ds_bpermute_b32 v33, v59, v32
	s_waitcnt lgkmcnt(0)
	v_add_f32_e32 v32, v32, v33
	ds_bpermute_b32 v33, v60, v32
	s_waitcnt lgkmcnt(0)
	v_add_f32_e32 v32, v32, v33
	ds_bpermute_b32 v33, v61, v32
	s_waitcnt lgkmcnt(0)
	v_add_f32_e32 v32, v32, v33
	ds_bpermute_b32 v33, v62, v32
	s_waitcnt lgkmcnt(0)
	v_add_f32_e32 v32, v32, v33
	v_fmamk_f32 v32, v32, 0x3a800000, v69
	v_mul_f32_e32 v33, 0x4b800000, v32
	v_cmp_gt_f32_e32 vcc, s19, v32
	s_nop 1
	v_cndmask_b32_e32 v32, v32, v33, vcc
	v_rsq_f32_e32 v32, v32
	s_nop 0
	v_mul_f32_e32 v33, 0x45800000, v32
	v_cndmask_b32_e32 v32, v32, v33, vcc
	v_pk_mul_f32 v[70:71], v[214:215], v[32:33] op_sel_hi:[1,0]
	v_pk_mul_f32 v[72:73], v[216:217], v[32:33] op_sel_hi:[1,0]
	v_pk_mul_f32 v[74:75], v[218:219], v[32:33] op_sel_hi:[1,0]
	v_pk_mul_f32 v[76:77], v[220:221], v[32:33] op_sel_hi:[1,0]
	v_pk_mul_f32 v[78:79], v[222:223], v[32:33] op_sel_hi:[1,0]
	v_pk_mul_f32 v[80:81], v[224:225], v[32:33] op_sel_hi:[1,0]
	v_pk_mul_f32 v[82:83], v[226:227], v[32:33] op_sel_hi:[1,0]
	v_pk_mul_f32 v[32:33], v[228:229], v[32:33] op_sel_hi:[1,0]
	v_pk_fma_f32 v[70:71], v[50:51], v[70:71], v[22:23]
	v_pk_fma_f32 v[72:73], v[4:5], v[72:73], v[24:25]
	v_pk_fma_f32 v[74:75], v[6:7], v[74:75], v[14:15]
	v_pk_fma_f32 v[76:77], v[2:3], v[76:77], v[16:17]
	v_pk_fma_f32 v[78:79], v[12:13], v[78:79], v[26:27]
	v_pk_fma_f32 v[80:81], v[8:9], v[80:81], v[28:29]
	v_pk_fma_f32 v[82:83], v[30:31], v[82:83], v[18:19]
	v_pk_fma_f32 v[32:33], v[10:11], v[32:33], v[20:21]
	v_cvt_pk_bf16_f32 v70, v70, v71
	v_cvt_pk_bf16_f32 v71, v72, v73
	v_cvt_pk_bf16_f32 v72, v74, v75
	v_cvt_pk_bf16_f32 v73, v76, v77
	v_cvt_pk_bf16_f32 v74, v78, v79
	v_cvt_pk_bf16_f32 v75, v80, v81
	v_cvt_pk_bf16_f32 v76, v82, v83
	v_cvt_pk_bf16_f32 v77, v32, v33
	global_store_dwordx2 v[104:105], v[70:71], off
	global_store_dwordx2 v[104:105], v[72:73], off offset:512
	global_store_dwordx2 v[104:105], v[74:75], off offset:1024
	global_store_dwordx2 v[104:105], v[76:77], off offset:1536
	s_waitcnt vmcnt(15)
	v_mov_b32_e32 v90, v231
	s_waitcnt vmcnt(14)
	v_mov_b32_e32 v91, v235
	v_mov_b32_e32 v88, v230
	v_mov_b32_e32 v89, v234
	s_waitcnt vmcnt(13)
	v_mov_b32_e32 v98, v239
	s_waitcnt vmcnt(12)
	v_mov_b32_e32 v99, v201
	v_pk_mul_f32 v[90:91], v[90:91], v[90:91]
	v_mov_b32_e32 v32, v232
	v_mov_b32_e32 v33, v236
	v_mov_b32_e32 v96, v238
	v_mov_b32_e32 v97, v200
	v_pk_mul_f32 v[98:99], v[98:99], v[98:99]
	v_pk_fma_f32 v[88:89], v[88:89], v[88:89], v[90:91]
	v_mov_b32_e32 v86, v233
	v_mov_b32_e32 v87, v237
	v_mov_b32_e32 v92, v240
	v_mov_b32_e32 v93, v202
	v_pk_fma_f32 v[90:91], v[96:97], v[96:97], v[98:99]
	v_pk_fma_f32 v[32:33], v[32:33], v[32:33], v[88:89]
	v_mov_b32_e32 v94, v241
	v_mov_b32_e32 v95, v203
	v_pk_fma_f32 v[88:89], v[92:93], v[92:93], v[90:91]
	v_pk_fma_f32 v[32:33], v[86:87], v[86:87], v[32:33]
	v_pk_fma_f32 v[86:87], v[94:95], v[94:95], v[88:89]
	v_add_f32_e32 v32, v32, v33
	v_add_f32_e32 v32, v32, v86
	v_add_f32_e32 v32, v32, v87
	ds_bpermute_b32 v33, v57, v32
	s_waitcnt lgkmcnt(0)
	v_add_f32_e32 v32, v32, v33
	ds_bpermute_b32 v33, v58, v32
	s_waitcnt lgkmcnt(0)
	v_add_f32_e32 v32, v32, v33
	ds_bpermute_b32 v33, v59, v32
	s_waitcnt lgkmcnt(0)
	v_add_f32_e32 v32, v32, v33
	ds_bpermute_b32 v33, v60, v32
	s_waitcnt lgkmcnt(0)
	v_add_f32_e32 v32, v32, v33
	ds_bpermute_b32 v33, v61, v32
	s_waitcnt lgkmcnt(0)
	v_add_f32_e32 v32, v32, v33
	ds_bpermute_b32 v33, v62, v32
	s_waitcnt lgkmcnt(0)
	v_add_f32_e32 v32, v32, v33
	v_fmamk_f32 v32, v32, 0x3a800000, v69
	v_mul_f32_e32 v33, 0x4b800000, v32
	v_cmp_gt_f32_e32 vcc, s19, v32
	s_nop 1
	v_cndmask_b32_e32 v32, v32, v33, vcc
	v_rsq_f32_e32 v32, v32
	s_nop 0
	v_mul_f32_e32 v33, 0x45800000, v32
	v_cndmask_b32_e32 v32, v32, v33, vcc
	v_pk_mul_f32 v[70:71], v[230:231], v[32:33] op_sel_hi:[1,0]
	v_pk_mul_f32 v[72:73], v[232:233], v[32:33] op_sel_hi:[1,0]
	v_pk_mul_f32 v[74:75], v[234:235], v[32:33] op_sel_hi:[1,0]
	v_pk_mul_f32 v[76:77], v[236:237], v[32:33] op_sel_hi:[1,0]
	v_pk_mul_f32 v[78:79], v[238:239], v[32:33] op_sel_hi:[1,0]
	v_pk_mul_f32 v[80:81], v[240:241], v[32:33] op_sel_hi:[1,0]
	v_pk_mul_f32 v[82:83], v[200:201], v[32:33] op_sel_hi:[1,0]
	v_pk_mul_f32 v[32:33], v[202:203], v[32:33] op_sel_hi:[1,0]
	v_pk_fma_f32 v[70:71], v[50:51], v[70:71], v[22:23]
	v_pk_fma_f32 v[72:73], v[4:5], v[72:73], v[24:25]
	v_pk_fma_f32 v[74:75], v[6:7], v[74:75], v[14:15]
	v_pk_fma_f32 v[76:77], v[2:3], v[76:77], v[16:17]
	v_pk_fma_f32 v[78:79], v[12:13], v[78:79], v[26:27]
	v_pk_fma_f32 v[80:81], v[8:9], v[80:81], v[28:29]
	v_pk_fma_f32 v[82:83], v[30:31], v[82:83], v[18:19]
	v_pk_fma_f32 v[32:33], v[10:11], v[32:33], v[20:21]
	v_cvt_pk_bf16_f32 v70, v70, v71
	v_cvt_pk_bf16_f32 v71, v72, v73
	v_cvt_pk_bf16_f32 v72, v74, v75
	v_cvt_pk_bf16_f32 v73, v76, v77
	v_cvt_pk_bf16_f32 v74, v78, v79
	v_cvt_pk_bf16_f32 v75, v80, v81
	v_cvt_pk_bf16_f32 v76, v82, v83
	v_cvt_pk_bf16_f32 v77, v32, v33
	global_store_dwordx2 v[54:55], v[70:71], off
	global_store_dwordx2 v[54:55], v[72:73], off offset:512
	global_store_dwordx2 v[54:55], v[74:75], off offset:1024
	global_store_dwordx2 v[54:55], v[76:77], off offset:1536
	v_lshlrev_b64 v[32:33], 11, v[48:49]
	v_cmp_lt_i32_e32 vcc, s20, v66
	s_or_b64 s[12:13], vcc, s[12:13]
	v_lshl_add_u64 v[32:33], v[38:39], 0, v[32:33]
	s_waitcnt vmcnt(15)
	v_mov_b32_e32 v86, v205
	s_waitcnt vmcnt(14)
	v_mov_b32_e32 v87, v209
	v_mov_b32_e32 v84, v204
	v_mov_b32_e32 v85, v208
	s_waitcnt vmcnt(13)
	v_mov_b32_e32 v94, v247
	s_waitcnt vmcnt(12)
	v_mov_b32_e32 v95, v251
	v_pk_mul_f32 v[86:87], v[86:87], v[86:87]
	v_mov_b32_e32 v48, v206
	v_mov_b32_e32 v49, v210
	v_mov_b32_e32 v92, v246
	v_mov_b32_e32 v93, v250
	v_pk_mul_f32 v[94:95], v[94:95], v[94:95]
	v_pk_fma_f32 v[84:85], v[84:85], v[84:85], v[86:87]
	v_mov_b32_e32 v82, v207
	v_mov_b32_e32 v83, v211
	v_mov_b32_e32 v88, v248
	v_mov_b32_e32 v89, v252
	v_pk_fma_f32 v[86:87], v[92:93], v[92:93], v[94:95]
	v_pk_fma_f32 v[48:49], v[48:49], v[48:49], v[84:85]
	v_mov_b32_e32 v90, v249
	v_mov_b32_e32 v91, v253
	v_pk_fma_f32 v[84:85], v[88:89], v[88:89], v[86:87]
	v_pk_fma_f32 v[48:49], v[82:83], v[82:83], v[48:49]
	v_pk_fma_f32 v[82:83], v[90:91], v[90:91], v[84:85]
	v_add_f32_e32 v48, v48, v49
	v_add_f32_e32 v48, v48, v82
	v_add_f32_e32 v48, v48, v83
	ds_bpermute_b32 v49, v57, v48
	s_waitcnt lgkmcnt(0)
	v_add_f32_e32 v48, v48, v49
	ds_bpermute_b32 v49, v58, v48
	s_waitcnt lgkmcnt(0)
	v_add_f32_e32 v48, v48, v49
	ds_bpermute_b32 v49, v59, v48
	s_waitcnt lgkmcnt(0)
	v_add_f32_e32 v48, v48, v49
	ds_bpermute_b32 v49, v60, v48
	s_waitcnt lgkmcnt(0)
	v_add_f32_e32 v48, v48, v49
	ds_bpermute_b32 v49, v61, v48
	s_waitcnt lgkmcnt(0)
	v_add_f32_e32 v48, v48, v49
	ds_bpermute_b32 v49, v62, v48
	s_waitcnt lgkmcnt(0)
	v_add_f32_e32 v48, v48, v49
	v_fmamk_f32 v48, v48, 0x3a800000, v69
	v_mul_f32_e32 v49, 0x4b800000, v48
	v_cmp_gt_f32_e32 vcc, s19, v48
	s_nop 1
	v_cndmask_b32_e32 v48, v48, v49, vcc
	v_rsq_f32_e32 v48, v48
	s_nop 0
	v_mul_f32_e32 v49, 0x45800000, v48
	v_cndmask_b32_e32 v48, v48, v49, vcc
	v_pk_mul_f32 v[70:71], v[204:205], v[48:49] op_sel_hi:[1,0]
	v_pk_mul_f32 v[72:73], v[206:207], v[48:49] op_sel_hi:[1,0]
	v_pk_mul_f32 v[74:75], v[208:209], v[48:49] op_sel_hi:[1,0]
	v_pk_mul_f32 v[76:77], v[210:211], v[48:49] op_sel_hi:[1,0]
	v_pk_mul_f32 v[78:79], v[246:247], v[48:49] op_sel_hi:[1,0]
	v_pk_mul_f32 v[80:81], v[248:249], v[48:49] op_sel_hi:[1,0]
	v_pk_mul_f32 v[52:53], v[250:251], v[48:49] op_sel_hi:[1,0]
	v_pk_mul_f32 v[48:49], v[252:253], v[48:49] op_sel_hi:[1,0]
	v_pk_fma_f32 v[22:23], v[50:51], v[70:71], v[22:23]
	v_pk_fma_f32 v[4:5], v[4:5], v[72:73], v[24:25]
	v_pk_fma_f32 v[6:7], v[6:7], v[74:75], v[14:15]
	v_pk_fma_f32 v[2:3], v[2:3], v[76:77], v[16:17]
	v_pk_fma_f32 v[12:13], v[12:13], v[78:79], v[26:27]
	v_pk_fma_f32 v[8:9], v[8:9], v[80:81], v[28:29]
	v_pk_fma_f32 v[14:15], v[30:31], v[52:53], v[18:19]
	v_pk_fma_f32 v[10:11], v[10:11], v[48:49], v[20:21]
	v_cvt_pk_bf16_f32 v16, v22, v23
	v_cvt_pk_bf16_f32 v17, v4, v5
	v_cvt_pk_bf16_f32 v4, v6, v7
	v_cvt_pk_bf16_f32 v5, v2, v3
	v_cvt_pk_bf16_f32 v2, v12, v13
	v_cvt_pk_bf16_f32 v3, v8, v9
	v_cvt_pk_bf16_f32 v6, v14, v15
	v_cvt_pk_bf16_f32 v7, v10, v11
	global_store_dwordx2 v[32:33], v[16:17], off
	global_store_dwordx2 v[32:33], v[4:5], off offset:512
	global_store_dwordx2 v[32:33], v[2:3], off offset:1024
	global_store_dwordx2 v[32:33], v[6:7], off offset:1536
	s_andn2_b64 exec, exec, s[12:13]
	s_cbranch_execnz .LBB0_134
